# ple-gate multiply via v_fma_mix_f32 from the loaded fp16 words (no conversions)
# baseline (speedup 1.0000x reference)
; __device__ __forceinline__ f32x4 sig4(const f32x4 v) { return (f32x4){sigmoidf_(v[0]), sigmoidf_(v[1]), sigmoidf_(v[2]), sigmoidf_(v[3])}; }
;     __device__ __forceinline__ void ple_gate(f32x4 (&acc)[2][2][4][2], const GUnit& u, int wr, int wc, int fr, int fq) const {
;         const f16* ple = (const f16*)(ws + WS_PLE); const int grow0 = u.pm * 256 + wr * 64 + fr, gcol0 = u.pn * 256 + wc * 32 + 8 * fq;
;         u32x4 pw[2][4][2];
; #pragma unroll
;         for (int ai = 0; ai < 2; ++ai)
; #pragma unroll
;             for (int m = 0; m < 4; ++m)
; #pragma unroll
;                 for (int bj = 0; bj < 2; ++bj) pw[ai][m][bj] = *(const u32x4*)(ple + (size_t)(grow0 + ai * 128 + m * 16) * 1024 + gcol0 + bj * 128);
;         asm volatile("" ::: "memory");
; #pragma unroll
;         for (int ai = 0; ai < 2; ++ai)
; #pragma unroll
;             for (int m = 0; m < 4; ++m)
; #pragma unroll
;                 for (int bj = 0; bj < 2; ++bj) { f32x4 p0, p1; unpk8(pw[ai][m][bj], p0, p1); acc[ai][bj][m][0] = sig4(acc[ai][bj][m][0]) * p0; acc[ai][bj][m][1] = sig4(acc[ai][bj][m][1]) * p1; }
.LBB0_380:
	s_lshl_b32 s8, s37, 8
	s_add_i32 s8, s8, s48
	v_or_b32_e32 v132, s8, v185
	s_lshl_b32 s8, s34, 8
	v_readlane_b32 s9, v251, 28
	s_or_b32 s8, s8, s9
	v_lshl_add_u32 v134, v35, 3, s8
	v_readlane_b32 s8, v252, 3
	v_readlane_b32 s9, v252, 4
	v_ashrrev_i32_e32 v135, 31, v134
	v_ashrrev_i32_e32 v133, 31, v132
	s_mov_b32 s98, 0xbfb8aa3b
	v_lshl_add_u64 v[134:135], v[134:135], 1, s[8:9]
	v_lshlrev_b64 v[132:133], 11, v[132:133]
	v_lshl_add_u64 v[132:133], v[134:135], 0, v[132:133]
	global_load_dwordx4 v[136:139], v[132:133], off
	global_load_dwordx4 v[140:143], v[132:133], off offset:256
	v_add_co_u32_e32 v134, vcc, 0x8000, v132
	v_addc_co_u32_e32 v135, vcc, 0, v133, vcc
	global_load_dwordx4 v[144:147], v[134:135], off
	global_load_dwordx4 v[148:151], v[134:135], off offset:256
	v_add_co_u32_e32 v134, vcc, 0x10000, v132
	v_addc_co_u32_e32 v135, vcc, 0, v133, vcc
	global_load_dwordx4 v[152:155], v[134:135], off
	global_load_dwordx4 v[156:159], v[134:135], off offset:256
	v_add_co_u32_e32 v134, vcc, 0x18000, v132
	v_addc_co_u32_e32 v135, vcc, 0, v133, vcc
	global_load_dwordx4 v[160:163], v[134:135], off
	global_load_dwordx4 v[164:167], v[134:135], off offset:256
	v_add_co_u32_e32 v134, vcc, 0x40000, v132
	v_addc_co_u32_e32 v135, vcc, 0, v133, vcc
	global_load_dwordx4 v[168:171], v[134:135], off
	global_load_dwordx4 v[172:175], v[134:135], off offset:256
	v_add_co_u32_e32 v134, vcc, 0x48000, v132
	v_addc_co_u32_e32 v135, vcc, 0, v133, vcc
	global_load_dwordx4 v[176:179], v[134:135], off
	global_load_dwordx4 v[180:183], v[134:135], off offset:256
	v_add_co_u32_e32 v134, vcc, 0x50000, v132
	v_addc_co_u32_e32 v135, vcc, 0, v133, vcc
	global_load_dwordx4 v[190:193], v[134:135], off
	global_load_dwordx4 v[198:201], v[134:135], off offset:256
	v_add_co_u32_e32 v134, vcc, 0x58000, v132
	v_addc_co_u32_e32 v135, vcc, 0, v133, vcc
	global_load_dwordx4 v[204:207], v[134:135], off
	global_load_dwordx4 v[208:211], v[134:135], off offset:256
	v_pk_mul_f32 v[128:129], v[128:129], s[98:99] op_sel_hi:[1,0]
	v_pk_mul_f32 v[130:131], v[130:131], s[98:99] op_sel_hi:[1,0]
	v_pk_mul_f32 v[124:125], v[124:125], s[98:99] op_sel_hi:[1,0]
	v_pk_mul_f32 v[126:127], v[126:127], s[98:99] op_sel_hi:[1,0]
	v_exp_f32_e32 v128, v128
	v_exp_f32_e32 v124, v124
	v_exp_f32_e32 v129, v129
	v_exp_f32_e32 v125, v125
	v_exp_f32_e32 v130, v130
	v_exp_f32_e32 v126, v126
	v_exp_f32_e32 v131, v131
	v_exp_f32_e32 v127, v127
	v_pk_add_f32 v[128:129], v[128:129], 1.0 op_sel_hi:[1,0]
	v_pk_add_f32 v[130:131], v[130:131], 1.0 op_sel_hi:[1,0]
	v_pk_add_f32 v[124:125], v[124:125], 1.0 op_sel_hi:[1,0]
	v_pk_add_f32 v[126:127], v[126:127], 1.0 op_sel_hi:[1,0]
	v_rcp_f32_e32 v128, v128
	v_rcp_f32_e32 v124, v124
	v_rcp_f32_e32 v129, v129
	v_rcp_f32_e32 v125, v125
	v_rcp_f32_e32 v130, v130
	v_rcp_f32_e32 v126, v126
	v_rcp_f32_e32 v131, v131
	v_rcp_f32_e32 v127, v127
	v_pk_mul_f32 v[120:121], v[120:121], s[98:99] op_sel_hi:[1,0]
	v_pk_mul_f32 v[122:123], v[122:123], s[98:99] op_sel_hi:[1,0]
	v_pk_mul_f32 v[116:117], v[116:117], s[98:99] op_sel_hi:[1,0]
	v_pk_mul_f32 v[118:119], v[118:119], s[98:99] op_sel_hi:[1,0]
	v_exp_f32_e32 v120, v120
	v_exp_f32_e32 v116, v116
	v_exp_f32_e32 v121, v121
	v_exp_f32_e32 v117, v117
	v_exp_f32_e32 v122, v122
	v_exp_f32_e32 v118, v118
	v_exp_f32_e32 v123, v123
	v_exp_f32_e32 v119, v119
	v_pk_add_f32 v[120:121], v[120:121], 1.0 op_sel_hi:[1,0]
	v_pk_add_f32 v[122:123], v[122:123], 1.0 op_sel_hi:[1,0]
	v_pk_add_f32 v[116:117], v[116:117], 1.0 op_sel_hi:[1,0]
	v_pk_add_f32 v[118:119], v[118:119], 1.0 op_sel_hi:[1,0]
	v_rcp_f32_e32 v120, v120
	v_rcp_f32_e32 v116, v116
	v_rcp_f32_e32 v121, v121
	v_rcp_f32_e32 v117, v117
	v_rcp_f32_e32 v122, v122
	v_rcp_f32_e32 v118, v118
	v_rcp_f32_e32 v123, v123
	v_rcp_f32_e32 v119, v119
	v_pk_mul_f32 v[112:113], v[112:113], s[98:99] op_sel_hi:[1,0]
	v_pk_mul_f32 v[114:115], v[114:115], s[98:99] op_sel_hi:[1,0]
	v_pk_mul_f32 v[108:109], v[108:109], s[98:99] op_sel_hi:[1,0]
	v_pk_mul_f32 v[110:111], v[110:111], s[98:99] op_sel_hi:[1,0]
	v_exp_f32_e32 v112, v112
	v_exp_f32_e32 v108, v108
	v_exp_f32_e32 v113, v113
	v_exp_f32_e32 v109, v109
	v_exp_f32_e32 v114, v114
	v_exp_f32_e32 v110, v110
	v_exp_f32_e32 v115, v115
	v_exp_f32_e32 v111, v111
	v_pk_add_f32 v[112:113], v[112:113], 1.0 op_sel_hi:[1,0]
	v_pk_add_f32 v[114:115], v[114:115], 1.0 op_sel_hi:[1,0]
	v_pk_add_f32 v[108:109], v[108:109], 1.0 op_sel_hi:[1,0]
	v_pk_add_f32 v[110:111], v[110:111], 1.0 op_sel_hi:[1,0]
	v_rcp_f32_e32 v112, v112
	v_rcp_f32_e32 v108, v108
	v_rcp_f32_e32 v113, v113
	v_rcp_f32_e32 v109, v109
	v_rcp_f32_e32 v114, v114
	v_rcp_f32_e32 v110, v110
	v_rcp_f32_e32 v115, v115
	v_rcp_f32_e32 v111, v111
	v_pk_mul_f32 v[104:105], v[104:105], s[98:99] op_sel_hi:[1,0]
	v_pk_mul_f32 v[106:107], v[106:107], s[98:99] op_sel_hi:[1,0]
	v_pk_mul_f32 v[100:101], v[100:101], s[98:99] op_sel_hi:[1,0]
	v_pk_mul_f32 v[102:103], v[102:103], s[98:99] op_sel_hi:[1,0]
	v_exp_f32_e32 v104, v104
	v_exp_f32_e32 v100, v100
	v_exp_f32_e32 v105, v105
	v_exp_f32_e32 v101, v101
	v_exp_f32_e32 v106, v106
	v_exp_f32_e32 v102, v102
	v_exp_f32_e32 v107, v107
	v_exp_f32_e32 v103, v103
	v_pk_add_f32 v[104:105], v[104:105], 1.0 op_sel_hi:[1,0]
	v_pk_add_f32 v[106:107], v[106:107], 1.0 op_sel_hi:[1,0]
	v_pk_add_f32 v[100:101], v[100:101], 1.0 op_sel_hi:[1,0]
	v_pk_add_f32 v[102:103], v[102:103], 1.0 op_sel_hi:[1,0]
	v_rcp_f32_e32 v104, v104
	v_rcp_f32_e32 v100, v100
	v_rcp_f32_e32 v105, v105
	v_rcp_f32_e32 v101, v101
	v_rcp_f32_e32 v106, v106
	v_rcp_f32_e32 v102, v102
	v_rcp_f32_e32 v107, v107
	v_rcp_f32_e32 v103, v103
	v_pk_mul_f32 v[96:97], v[96:97], s[98:99] op_sel_hi:[1,0]
; __device__ __forceinline__ float sigmoidf_(float x) { return __builtin_amdgcn_rcpf(1.0f + __expf(-x)); }
; __device__ __forceinline__ f32x4 sig4(const f32x4 v) { return (f32x4){sigmoidf_(v[0]), sigmoidf_(v[1]), sigmoidf_(v[2]), sigmoidf_(v[3])}; }
;     __device__ __forceinline__ void ple_gate(f32x4 (&acc)[2][2][4][2], const GUnit& u, int wr, int wc, int fr, int fq) const {
;     ...
;                 for (int bj = 0; bj < 2; ++bj) { f32x4 p0, p1; unpk8(pw[ai][m][bj], p0, p1); acc[ai][bj][m][0] = sig4(acc[ai][bj][m][0]) * p0; acc[ai][bj][m][1] = sig4(acc[ai][bj][m][1]) * p1; }
	v_pk_mul_f32 v[98:99], v[98:99], s[98:99] op_sel_hi:[1,0]
	v_pk_mul_f32 v[92:93], v[92:93], s[98:99] op_sel_hi:[1,0]
	v_pk_mul_f32 v[94:95], v[94:95], s[98:99] op_sel_hi:[1,0]
	v_exp_f32_e32 v96, v96
	v_exp_f32_e32 v92, v92
	v_exp_f32_e32 v97, v97
	v_exp_f32_e32 v93, v93
	v_exp_f32_e32 v98, v98
	v_exp_f32_e32 v94, v94
	v_exp_f32_e32 v99, v99
	v_exp_f32_e32 v95, v95
	v_pk_add_f32 v[96:97], v[96:97], 1.0 op_sel_hi:[1,0]
	v_pk_add_f32 v[98:99], v[98:99], 1.0 op_sel_hi:[1,0]
	v_pk_add_f32 v[92:93], v[92:93], 1.0 op_sel_hi:[1,0]
	v_pk_add_f32 v[94:95], v[94:95], 1.0 op_sel_hi:[1,0]
	v_rcp_f32_e32 v96, v96
	v_rcp_f32_e32 v92, v92
	v_rcp_f32_e32 v97, v97
	v_rcp_f32_e32 v93, v93
	v_rcp_f32_e32 v98, v98
	v_rcp_f32_e32 v94, v94
	v_rcp_f32_e32 v99, v99
	v_rcp_f32_e32 v95, v95
	v_pk_mul_f32 v[88:89], v[88:89], s[98:99] op_sel_hi:[1,0]
	v_pk_mul_f32 v[90:91], v[90:91], s[98:99] op_sel_hi:[1,0]
	v_pk_mul_f32 v[84:85], v[84:85], s[98:99] op_sel_hi:[1,0]
	v_pk_mul_f32 v[86:87], v[86:87], s[98:99] op_sel_hi:[1,0]
	v_exp_f32_e32 v88, v88
	v_exp_f32_e32 v84, v84
	v_exp_f32_e32 v89, v89
	v_exp_f32_e32 v85, v85
	v_exp_f32_e32 v90, v90
	v_exp_f32_e32 v86, v86
	v_exp_f32_e32 v91, v91
	v_exp_f32_e32 v87, v87
	v_pk_add_f32 v[88:89], v[88:89], 1.0 op_sel_hi:[1,0]
	v_pk_add_f32 v[90:91], v[90:91], 1.0 op_sel_hi:[1,0]
	v_pk_add_f32 v[84:85], v[84:85], 1.0 op_sel_hi:[1,0]
	v_pk_add_f32 v[86:87], v[86:87], 1.0 op_sel_hi:[1,0]
	v_rcp_f32_e32 v88, v88
	v_rcp_f32_e32 v84, v84
	v_rcp_f32_e32 v89, v89
	v_rcp_f32_e32 v85, v85
	v_rcp_f32_e32 v90, v90
	v_rcp_f32_e32 v86, v86
	v_rcp_f32_e32 v91, v91
	v_rcp_f32_e32 v87, v87
	v_pk_mul_f32 v[80:81], v[80:81], s[98:99] op_sel_hi:[1,0]
	v_pk_mul_f32 v[82:83], v[82:83], s[98:99] op_sel_hi:[1,0]
	v_pk_mul_f32 v[76:77], v[76:77], s[98:99] op_sel_hi:[1,0]
	v_pk_mul_f32 v[78:79], v[78:79], s[98:99] op_sel_hi:[1,0]
	v_exp_f32_e32 v80, v80
	v_exp_f32_e32 v76, v76
	v_exp_f32_e32 v81, v81
	v_exp_f32_e32 v77, v77
	v_exp_f32_e32 v82, v82
	v_exp_f32_e32 v78, v78
	v_exp_f32_e32 v83, v83
	v_exp_f32_e32 v79, v79
	v_pk_add_f32 v[80:81], v[80:81], 1.0 op_sel_hi:[1,0]
	v_pk_add_f32 v[82:83], v[82:83], 1.0 op_sel_hi:[1,0]
	v_pk_add_f32 v[76:77], v[76:77], 1.0 op_sel_hi:[1,0]
	v_pk_add_f32 v[78:79], v[78:79], 1.0 op_sel_hi:[1,0]
	v_rcp_f32_e32 v80, v80
	v_rcp_f32_e32 v76, v76
	v_rcp_f32_e32 v81, v81
	v_rcp_f32_e32 v77, v77
	v_rcp_f32_e32 v82, v82
	v_rcp_f32_e32 v78, v78
	v_rcp_f32_e32 v83, v83
	v_rcp_f32_e32 v79, v79
	v_pk_mul_f32 v[72:73], v[72:73], s[98:99] op_sel_hi:[1,0]
	v_pk_mul_f32 v[74:75], v[74:75], s[98:99] op_sel_hi:[1,0]
	v_pk_mul_f32 v[68:69], v[68:69], s[98:99] op_sel_hi:[1,0]
	v_pk_mul_f32 v[70:71], v[70:71], s[98:99] op_sel_hi:[1,0]
	v_exp_f32_e32 v72, v72
	v_exp_f32_e32 v68, v68
	v_exp_f32_e32 v73, v73
	v_exp_f32_e32 v69, v69
	v_exp_f32_e32 v74, v74
	v_exp_f32_e32 v70, v70
	v_exp_f32_e32 v75, v75
	v_exp_f32_e32 v71, v71
	v_pk_add_f32 v[72:73], v[72:73], 1.0 op_sel_hi:[1,0]
	v_pk_add_f32 v[74:75], v[74:75], 1.0 op_sel_hi:[1,0]
	v_pk_add_f32 v[68:69], v[68:69], 1.0 op_sel_hi:[1,0]
	v_pk_add_f32 v[70:71], v[70:71], 1.0 op_sel_hi:[1,0]
	v_rcp_f32_e32 v72, v72
	v_rcp_f32_e32 v68, v68
	v_rcp_f32_e32 v73, v73
	v_rcp_f32_e32 v69, v69
	v_rcp_f32_e32 v74, v74
	v_rcp_f32_e32 v70, v70
	v_rcp_f32_e32 v75, v75
	v_rcp_f32_e32 v71, v71
	v_pk_mul_f32 v[64:65], v[64:65], s[98:99] op_sel_hi:[1,0]
	v_pk_mul_f32 v[66:67], v[66:67], s[98:99] op_sel_hi:[1,0]
	v_pk_mul_f32 v[60:61], v[60:61], s[98:99] op_sel_hi:[1,0]
	v_pk_mul_f32 v[62:63], v[62:63], s[98:99] op_sel_hi:[1,0]
	v_exp_f32_e32 v64, v64
	v_exp_f32_e32 v60, v60
	v_exp_f32_e32 v65, v65
	v_exp_f32_e32 v61, v61
	v_exp_f32_e32 v66, v66
	v_exp_f32_e32 v62, v62
	v_exp_f32_e32 v67, v67
	v_exp_f32_e32 v63, v63
	v_pk_add_f32 v[64:65], v[64:65], 1.0 op_sel_hi:[1,0]
	v_pk_add_f32 v[66:67], v[66:67], 1.0 op_sel_hi:[1,0]
	v_pk_add_f32 v[60:61], v[60:61], 1.0 op_sel_hi:[1,0]
	v_pk_add_f32 v[62:63], v[62:63], 1.0 op_sel_hi:[1,0]
	v_rcp_f32_e32 v64, v64
	v_rcp_f32_e32 v60, v60
	v_rcp_f32_e32 v65, v65
	v_rcp_f32_e32 v61, v61
	v_rcp_f32_e32 v66, v66
	v_rcp_f32_e32 v62, v62
	v_rcp_f32_e32 v67, v67
	v_rcp_f32_e32 v63, v63
	v_pk_mul_f32 v[56:57], v[56:57], s[98:99] op_sel_hi:[1,0]
	v_pk_mul_f32 v[58:59], v[58:59], s[98:99] op_sel_hi:[1,0]
	v_pk_mul_f32 v[52:53], v[52:53], s[98:99] op_sel_hi:[1,0]
	v_pk_mul_f32 v[54:55], v[54:55], s[98:99] op_sel_hi:[1,0]
	v_exp_f32_e32 v56, v56
	v_exp_f32_e32 v52, v52
	v_exp_f32_e32 v57, v57
	v_exp_f32_e32 v53, v53
	v_exp_f32_e32 v58, v58
	v_exp_f32_e32 v54, v54
	v_exp_f32_e32 v59, v59
	v_exp_f32_e32 v55, v55
	v_pk_add_f32 v[56:57], v[56:57], 1.0 op_sel_hi:[1,0]
	v_pk_add_f32 v[58:59], v[58:59], 1.0 op_sel_hi:[1,0]
	v_pk_add_f32 v[52:53], v[52:53], 1.0 op_sel_hi:[1,0]
	v_pk_add_f32 v[54:55], v[54:55], 1.0 op_sel_hi:[1,0]
	v_rcp_f32_e32 v56, v56
	v_rcp_f32_e32 v52, v52
	v_rcp_f32_e32 v57, v57
	v_rcp_f32_e32 v53, v53
	v_rcp_f32_e32 v58, v58
	v_rcp_f32_e32 v54, v54
	v_rcp_f32_e32 v59, v59
	v_rcp_f32_e32 v55, v55
	v_pk_mul_f32 v[48:49], v[48:49], s[98:99] op_sel_hi:[1,0]
	v_pk_mul_f32 v[50:51], v[50:51], s[98:99] op_sel_hi:[1,0]
	v_pk_mul_f32 v[44:45], v[44:45], s[98:99] op_sel_hi:[1,0]
	v_pk_mul_f32 v[46:47], v[46:47], s[98:99] op_sel_hi:[1,0]
	v_exp_f32_e32 v48, v48
	v_exp_f32_e32 v44, v44
	v_exp_f32_e32 v49, v49
	v_exp_f32_e32 v45, v45
	v_exp_f32_e32 v50, v50
	v_exp_f32_e32 v46, v46
	v_exp_f32_e32 v51, v51
	v_exp_f32_e32 v47, v47
	v_pk_add_f32 v[48:49], v[48:49], 1.0 op_sel_hi:[1,0]
	v_pk_add_f32 v[50:51], v[50:51], 1.0 op_sel_hi:[1,0]
	v_pk_add_f32 v[44:45], v[44:45], 1.0 op_sel_hi:[1,0]
	v_pk_add_f32 v[46:47], v[46:47], 1.0 op_sel_hi:[1,0]
	v_rcp_f32_e32 v48, v48
	v_rcp_f32_e32 v44, v44
; __device__ __forceinline__ float sigmoidf_(float x) { return __builtin_amdgcn_rcpf(1.0f + __expf(-x)); }
; __device__ __forceinline__ f32x4 sig4(const f32x4 v) { return (f32x4){sigmoidf_(v[0]), sigmoidf_(v[1]), sigmoidf_(v[2]), sigmoidf_(v[3])}; }
;     __device__ __forceinline__ void ple_gate(f32x4 (&acc)[2][2][4][2], const GUnit& u, int wr, int wc, int fr, int fq) const {
;     ...
;                 for (int bj = 0; bj < 2; ++bj) { f32x4 p0, p1; unpk8(pw[ai][m][bj], p0, p1); acc[ai][bj][m][0] = sig4(acc[ai][bj][m][0]) * p0; acc[ai][bj][m][1] = sig4(acc[ai][bj][m][1]) * p1; }
	v_rcp_f32_e32 v49, v49
	v_rcp_f32_e32 v45, v45
	v_rcp_f32_e32 v50, v50
	v_rcp_f32_e32 v46, v46
	v_rcp_f32_e32 v51, v51
	v_rcp_f32_e32 v47, v47
	v_pk_mul_f32 v[40:41], v[40:41], s[98:99] op_sel_hi:[1,0]
	v_pk_mul_f32 v[42:43], v[42:43], s[98:99] op_sel_hi:[1,0]
	v_pk_mul_f32 v[36:37], v[36:37], s[98:99] op_sel_hi:[1,0]
	v_pk_mul_f32 v[38:39], v[38:39], s[98:99] op_sel_hi:[1,0]
	v_exp_f32_e32 v40, v40
	v_exp_f32_e32 v36, v36
	v_exp_f32_e32 v41, v41
	v_exp_f32_e32 v37, v37
	v_exp_f32_e32 v42, v42
	v_exp_f32_e32 v38, v38
	v_exp_f32_e32 v43, v43
	v_exp_f32_e32 v39, v39
	v_pk_add_f32 v[40:41], v[40:41], 1.0 op_sel_hi:[1,0]
	v_pk_add_f32 v[42:43], v[42:43], 1.0 op_sel_hi:[1,0]
	v_pk_add_f32 v[36:37], v[36:37], 1.0 op_sel_hi:[1,0]
	v_pk_add_f32 v[38:39], v[38:39], 1.0 op_sel_hi:[1,0]
	v_rcp_f32_e32 v40, v40
	v_rcp_f32_e32 v36, v36
	v_rcp_f32_e32 v41, v41
	v_rcp_f32_e32 v37, v37
	v_rcp_f32_e32 v42, v42
	v_rcp_f32_e32 v38, v38
	v_rcp_f32_e32 v43, v43
	v_rcp_f32_e32 v39, v39
	v_pk_mul_f32 v[28:29], v[28:29], s[98:99] op_sel_hi:[1,0]
	v_pk_mul_f32 v[30:31], v[30:31], s[98:99] op_sel_hi:[1,0]
	v_pk_mul_f32 v[24:25], v[24:25], s[98:99] op_sel_hi:[1,0]
	v_pk_mul_f32 v[26:27], v[26:27], s[98:99] op_sel_hi:[1,0]
	v_exp_f32_e32 v28, v28
	v_exp_f32_e32 v24, v24
	v_exp_f32_e32 v29, v29
	v_exp_f32_e32 v25, v25
	v_exp_f32_e32 v30, v30
	v_exp_f32_e32 v26, v26
	v_exp_f32_e32 v31, v31
	v_exp_f32_e32 v27, v27
	v_pk_add_f32 v[28:29], v[28:29], 1.0 op_sel_hi:[1,0]
	v_pk_add_f32 v[30:31], v[30:31], 1.0 op_sel_hi:[1,0]
	v_pk_add_f32 v[24:25], v[24:25], 1.0 op_sel_hi:[1,0]
	v_pk_add_f32 v[26:27], v[26:27], 1.0 op_sel_hi:[1,0]
	v_rcp_f32_e32 v28, v28
	v_rcp_f32_e32 v24, v24
	v_rcp_f32_e32 v29, v29
	v_rcp_f32_e32 v25, v25
	v_rcp_f32_e32 v30, v30
	v_rcp_f32_e32 v26, v26
	v_rcp_f32_e32 v31, v31
	v_rcp_f32_e32 v27, v27
	v_pk_mul_f32 v[20:21], v[20:21], s[98:99] op_sel_hi:[1,0]
	v_pk_mul_f32 v[22:23], v[22:23], s[98:99] op_sel_hi:[1,0]
	v_pk_mul_f32 v[16:17], v[16:17], s[98:99] op_sel_hi:[1,0]
	v_pk_mul_f32 v[18:19], v[18:19], s[98:99] op_sel_hi:[1,0]
	v_exp_f32_e32 v20, v20
	v_exp_f32_e32 v16, v16
	v_exp_f32_e32 v21, v21
	v_exp_f32_e32 v17, v17
	v_exp_f32_e32 v22, v22
	v_exp_f32_e32 v18, v18
	v_exp_f32_e32 v23, v23
	v_exp_f32_e32 v19, v19
	v_pk_add_f32 v[20:21], v[20:21], 1.0 op_sel_hi:[1,0]
	v_pk_add_f32 v[22:23], v[22:23], 1.0 op_sel_hi:[1,0]
	v_pk_add_f32 v[16:17], v[16:17], 1.0 op_sel_hi:[1,0]
	v_pk_add_f32 v[18:19], v[18:19], 1.0 op_sel_hi:[1,0]
	v_rcp_f32_e32 v20, v20
	v_rcp_f32_e32 v16, v16
	v_rcp_f32_e32 v21, v21
	v_rcp_f32_e32 v17, v17
	v_rcp_f32_e32 v22, v22
	v_rcp_f32_e32 v18, v18
	v_rcp_f32_e32 v23, v23
	v_rcp_f32_e32 v19, v19
	v_pk_mul_f32 v[12:13], v[12:13], s[98:99] op_sel_hi:[1,0]
	v_pk_mul_f32 v[14:15], v[14:15], s[98:99] op_sel_hi:[1,0]
	v_pk_mul_f32 v[8:9], v[8:9], s[98:99] op_sel_hi:[1,0]
	v_pk_mul_f32 v[10:11], v[10:11], s[98:99] op_sel_hi:[1,0]
	v_exp_f32_e32 v12, v12
	v_exp_f32_e32 v8, v8
	v_exp_f32_e32 v13, v13
	v_exp_f32_e32 v9, v9
	v_exp_f32_e32 v14, v14
	v_exp_f32_e32 v10, v10
	v_exp_f32_e32 v15, v15
	v_exp_f32_e32 v11, v11
	v_pk_add_f32 v[12:13], v[12:13], 1.0 op_sel_hi:[1,0]
	v_pk_add_f32 v[14:15], v[14:15], 1.0 op_sel_hi:[1,0]
	v_pk_add_f32 v[8:9], v[8:9], 1.0 op_sel_hi:[1,0]
	v_pk_add_f32 v[10:11], v[10:11], 1.0 op_sel_hi:[1,0]
	v_rcp_f32_e32 v12, v12
	v_rcp_f32_e32 v8, v8
	v_rcp_f32_e32 v13, v13
	v_rcp_f32_e32 v9, v9
	v_rcp_f32_e32 v14, v14
	v_rcp_f32_e32 v10, v10
	v_rcp_f32_e32 v15, v15
	v_rcp_f32_e32 v11, v11
	v_pk_mul_f32 v[4:5], v[4:5], s[98:99] op_sel_hi:[1,0]
	v_pk_mul_f32 v[6:7], v[6:7], s[98:99] op_sel_hi:[1,0]
	v_pk_mul_f32 v[0:1], v[0:1], s[98:99] op_sel_hi:[1,0]
	v_pk_mul_f32 v[2:3], v[2:3], s[98:99] op_sel_hi:[1,0]
	v_exp_f32_e32 v4, v4
	v_exp_f32_e32 v0, v0
	v_exp_f32_e32 v5, v5
	v_exp_f32_e32 v1, v1
	v_exp_f32_e32 v6, v6
	v_exp_f32_e32 v2, v2
	v_exp_f32_e32 v7, v7
	v_exp_f32_e32 v3, v3
	v_pk_add_f32 v[4:5], v[4:5], 1.0 op_sel_hi:[1,0]
	v_pk_add_f32 v[6:7], v[6:7], 1.0 op_sel_hi:[1,0]
	v_pk_add_f32 v[0:1], v[0:1], 1.0 op_sel_hi:[1,0]
	v_pk_add_f32 v[2:3], v[2:3], 1.0 op_sel_hi:[1,0]
	v_rcp_f32_e32 v4, v4
	v_rcp_f32_e32 v0, v0
	v_rcp_f32_e32 v5, v5
	v_rcp_f32_e32 v1, v1
	v_rcp_f32_e32 v6, v6
	v_rcp_f32_e32 v2, v2
	v_rcp_f32_e32 v7, v7
	v_rcp_f32_e32 v3, v3
	s_waitcnt vmcnt(15)
	v_fma_mix_f32 v128, v128, v136, 0 op_sel_hi:[0,1,0]
	v_fma_mix_f32 v129, v129, v136, 0 op_sel:[0,1,0] op_sel_hi:[0,1,0]
	v_fma_mix_f32 v130, v130, v137, 0 op_sel_hi:[0,1,0]
	v_fma_mix_f32 v131, v131, v137, 0 op_sel:[0,1,0] op_sel_hi:[0,1,0]
	v_fma_mix_f32 v124, v124, v138, 0 op_sel_hi:[0,1,0]
	v_fma_mix_f32 v125, v125, v138, 0 op_sel:[0,1,0] op_sel_hi:[0,1,0]
	v_fma_mix_f32 v126, v126, v139, 0 op_sel_hi:[0,1,0]
	v_fma_mix_f32 v127, v127, v139, 0 op_sel:[0,1,0] op_sel_hi:[0,1,0]
	s_waitcnt vmcnt(14)
	v_fma_mix_f32 v120, v120, v140, 0 op_sel_hi:[0,1,0]
	v_fma_mix_f32 v121, v121, v140, 0 op_sel:[0,1,0] op_sel_hi:[0,1,0]
	v_fma_mix_f32 v122, v122, v141, 0 op_sel_hi:[0,1,0]
	v_fma_mix_f32 v123, v123, v141, 0 op_sel:[0,1,0] op_sel_hi:[0,1,0]
	v_fma_mix_f32 v116, v116, v142, 0 op_sel_hi:[0,1,0]
	v_fma_mix_f32 v117, v117, v142, 0 op_sel:[0,1,0] op_sel_hi:[0,1,0]
	v_fma_mix_f32 v118, v118, v143, 0 op_sel_hi:[0,1,0]
	v_fma_mix_f32 v119, v119, v143, 0 op_sel:[0,1,0] op_sel_hi:[0,1,0]
	s_waitcnt vmcnt(13)
	v_fma_mix_f32 v112, v112, v144, 0 op_sel_hi:[0,1,0]
	v_fma_mix_f32 v113, v113, v144, 0 op_sel:[0,1,0] op_sel_hi:[0,1,0]
	v_fma_mix_f32 v114, v114, v145, 0 op_sel_hi:[0,1,0]
	v_fma_mix_f32 v115, v115, v145, 0 op_sel:[0,1,0] op_sel_hi:[0,1,0]
	v_fma_mix_f32 v108, v108, v146, 0 op_sel_hi:[0,1,0]
	v_fma_mix_f32 v109, v109, v146, 0 op_sel:[0,1,0] op_sel_hi:[0,1,0]
	v_fma_mix_f32 v110, v110, v147, 0 op_sel_hi:[0,1,0]
	v_fma_mix_f32 v111, v111, v147, 0 op_sel:[0,1,0] op_sel_hi:[0,1,0]
	s_waitcnt vmcnt(12)
; __device__ __forceinline__ f32x4 sig4(const f32x4 v) { return (f32x4){sigmoidf_(v[0]), sigmoidf_(v[1]), sigmoidf_(v[2]), sigmoidf_(v[3])}; }
;     __device__ __forceinline__ void ple_gate(f32x4 (&acc)[2][2][4][2], const GUnit& u, int wr, int wc, int fr, int fq) const {
;     ...
;                 for (int bj = 0; bj < 2; ++bj) { f32x4 p0, p1; unpk8(pw[ai][m][bj], p0, p1); acc[ai][bj][m][0] = sig4(acc[ai][bj][m][0]) * p0; acc[ai][bj][m][1] = sig4(acc[ai][bj][m][1]) * p1; }
	v_fma_mix_f32 v104, v104, v148, 0 op_sel_hi:[0,1,0]
	v_fma_mix_f32 v105, v105, v148, 0 op_sel:[0,1,0] op_sel_hi:[0,1,0]
	v_fma_mix_f32 v106, v106, v149, 0 op_sel_hi:[0,1,0]
	v_fma_mix_f32 v107, v107, v149, 0 op_sel:[0,1,0] op_sel_hi:[0,1,0]
	v_fma_mix_f32 v100, v100, v150, 0 op_sel_hi:[0,1,0]
	v_fma_mix_f32 v101, v101, v150, 0 op_sel:[0,1,0] op_sel_hi:[0,1,0]
	v_fma_mix_f32 v102, v102, v151, 0 op_sel_hi:[0,1,0]
	v_fma_mix_f32 v103, v103, v151, 0 op_sel:[0,1,0] op_sel_hi:[0,1,0]
	s_waitcnt vmcnt(11)
	v_fma_mix_f32 v96, v96, v152, 0 op_sel_hi:[0,1,0]
	v_fma_mix_f32 v97, v97, v152, 0 op_sel:[0,1,0] op_sel_hi:[0,1,0]
	v_fma_mix_f32 v98, v98, v153, 0 op_sel_hi:[0,1,0]
	v_fma_mix_f32 v99, v99, v153, 0 op_sel:[0,1,0] op_sel_hi:[0,1,0]
	v_fma_mix_f32 v92, v92, v154, 0 op_sel_hi:[0,1,0]
	v_fma_mix_f32 v93, v93, v154, 0 op_sel:[0,1,0] op_sel_hi:[0,1,0]
	v_fma_mix_f32 v94, v94, v155, 0 op_sel_hi:[0,1,0]
	v_fma_mix_f32 v95, v95, v155, 0 op_sel:[0,1,0] op_sel_hi:[0,1,0]
	s_waitcnt vmcnt(10)
	v_fma_mix_f32 v88, v88, v156, 0 op_sel_hi:[0,1,0]
	v_fma_mix_f32 v89, v89, v156, 0 op_sel:[0,1,0] op_sel_hi:[0,1,0]
	v_fma_mix_f32 v90, v90, v157, 0 op_sel_hi:[0,1,0]
	v_fma_mix_f32 v91, v91, v157, 0 op_sel:[0,1,0] op_sel_hi:[0,1,0]
	v_fma_mix_f32 v84, v84, v158, 0 op_sel_hi:[0,1,0]
	v_fma_mix_f32 v85, v85, v158, 0 op_sel:[0,1,0] op_sel_hi:[0,1,0]
	v_fma_mix_f32 v86, v86, v159, 0 op_sel_hi:[0,1,0]
	v_fma_mix_f32 v87, v87, v159, 0 op_sel:[0,1,0] op_sel_hi:[0,1,0]
	s_waitcnt vmcnt(9)
	v_fma_mix_f32 v80, v80, v160, 0 op_sel_hi:[0,1,0]
	v_fma_mix_f32 v81, v81, v160, 0 op_sel:[0,1,0] op_sel_hi:[0,1,0]
	v_fma_mix_f32 v82, v82, v161, 0 op_sel_hi:[0,1,0]
	v_fma_mix_f32 v83, v83, v161, 0 op_sel:[0,1,0] op_sel_hi:[0,1,0]
	v_fma_mix_f32 v76, v76, v162, 0 op_sel_hi:[0,1,0]
	v_fma_mix_f32 v77, v77, v162, 0 op_sel:[0,1,0] op_sel_hi:[0,1,0]
	v_fma_mix_f32 v78, v78, v163, 0 op_sel_hi:[0,1,0]
	v_fma_mix_f32 v79, v79, v163, 0 op_sel:[0,1,0] op_sel_hi:[0,1,0]
	s_waitcnt vmcnt(8)
	v_fma_mix_f32 v72, v72, v164, 0 op_sel_hi:[0,1,0]
	v_fma_mix_f32 v73, v73, v164, 0 op_sel:[0,1,0] op_sel_hi:[0,1,0]
	v_fma_mix_f32 v74, v74, v165, 0 op_sel_hi:[0,1,0]
	v_fma_mix_f32 v75, v75, v165, 0 op_sel:[0,1,0] op_sel_hi:[0,1,0]
	v_fma_mix_f32 v68, v68, v166, 0 op_sel_hi:[0,1,0]
	v_fma_mix_f32 v69, v69, v166, 0 op_sel:[0,1,0] op_sel_hi:[0,1,0]
	v_fma_mix_f32 v70, v70, v167, 0 op_sel_hi:[0,1,0]
	v_fma_mix_f32 v71, v71, v167, 0 op_sel:[0,1,0] op_sel_hi:[0,1,0]
	s_waitcnt vmcnt(7)
	v_fma_mix_f32 v64, v64, v168, 0 op_sel_hi:[0,1,0]
	v_fma_mix_f32 v65, v65, v168, 0 op_sel:[0,1,0] op_sel_hi:[0,1,0]
	v_fma_mix_f32 v66, v66, v169, 0 op_sel_hi:[0,1,0]
	v_fma_mix_f32 v67, v67, v169, 0 op_sel:[0,1,0] op_sel_hi:[0,1,0]
	v_fma_mix_f32 v60, v60, v170, 0 op_sel_hi:[0,1,0]
	v_fma_mix_f32 v61, v61, v170, 0 op_sel:[0,1,0] op_sel_hi:[0,1,0]
	v_fma_mix_f32 v62, v62, v171, 0 op_sel_hi:[0,1,0]
	v_fma_mix_f32 v63, v63, v171, 0 op_sel:[0,1,0] op_sel_hi:[0,1,0]
	s_waitcnt vmcnt(6)
	v_fma_mix_f32 v56, v56, v172, 0 op_sel_hi:[0,1,0]
	v_fma_mix_f32 v57, v57, v172, 0 op_sel:[0,1,0] op_sel_hi:[0,1,0]
	v_fma_mix_f32 v58, v58, v173, 0 op_sel_hi:[0,1,0]
	v_fma_mix_f32 v59, v59, v173, 0 op_sel:[0,1,0] op_sel_hi:[0,1,0]
	v_fma_mix_f32 v52, v52, v174, 0 op_sel_hi:[0,1,0]
	v_fma_mix_f32 v53, v53, v174, 0 op_sel:[0,1,0] op_sel_hi:[0,1,0]
	v_fma_mix_f32 v54, v54, v175, 0 op_sel_hi:[0,1,0]
	v_fma_mix_f32 v55, v55, v175, 0 op_sel:[0,1,0] op_sel_hi:[0,1,0]
	s_waitcnt vmcnt(5)
	v_fma_mix_f32 v48, v48, v176, 0 op_sel_hi:[0,1,0]
	v_fma_mix_f32 v49, v49, v176, 0 op_sel:[0,1,0] op_sel_hi:[0,1,0]
	v_fma_mix_f32 v50, v50, v177, 0 op_sel_hi:[0,1,0]
	v_fma_mix_f32 v51, v51, v177, 0 op_sel:[0,1,0] op_sel_hi:[0,1,0]
	v_fma_mix_f32 v44, v44, v178, 0 op_sel_hi:[0,1,0]
	v_fma_mix_f32 v45, v45, v178, 0 op_sel:[0,1,0] op_sel_hi:[0,1,0]
	v_fma_mix_f32 v46, v46, v179, 0 op_sel_hi:[0,1,0]
	v_fma_mix_f32 v47, v47, v179, 0 op_sel:[0,1,0] op_sel_hi:[0,1,0]
	s_waitcnt vmcnt(4)
	v_fma_mix_f32 v40, v40, v180, 0 op_sel_hi:[0,1,0]
	v_fma_mix_f32 v41, v41, v180, 0 op_sel:[0,1,0] op_sel_hi:[0,1,0]
	v_fma_mix_f32 v42, v42, v181, 0 op_sel_hi:[0,1,0]
	v_fma_mix_f32 v43, v43, v181, 0 op_sel:[0,1,0] op_sel_hi:[0,1,0]
	v_fma_mix_f32 v36, v36, v182, 0 op_sel_hi:[0,1,0]
	v_fma_mix_f32 v37, v37, v182, 0 op_sel:[0,1,0] op_sel_hi:[0,1,0]
	v_fma_mix_f32 v38, v38, v183, 0 op_sel_hi:[0,1,0]
	v_fma_mix_f32 v39, v39, v183, 0 op_sel:[0,1,0] op_sel_hi:[0,1,0]
	s_waitcnt vmcnt(3)
	v_fma_mix_f32 v28, v28, v190, 0 op_sel_hi:[0,1,0]
	v_fma_mix_f32 v29, v29, v190, 0 op_sel:[0,1,0] op_sel_hi:[0,1,0]
	v_fma_mix_f32 v30, v30, v191, 0 op_sel_hi:[0,1,0]
	v_fma_mix_f32 v31, v31, v191, 0 op_sel:[0,1,0] op_sel_hi:[0,1,0]
	v_fma_mix_f32 v24, v24, v192, 0 op_sel_hi:[0,1,0]
	v_fma_mix_f32 v25, v25, v192, 0 op_sel:[0,1,0] op_sel_hi:[0,1,0]
	v_fma_mix_f32 v26, v26, v193, 0 op_sel_hi:[0,1,0]
	v_fma_mix_f32 v27, v27, v193, 0 op_sel:[0,1,0] op_sel_hi:[0,1,0]
	s_waitcnt vmcnt(2)
	v_fma_mix_f32 v20, v20, v198, 0 op_sel_hi:[0,1,0]
	v_fma_mix_f32 v21, v21, v198, 0 op_sel:[0,1,0] op_sel_hi:[0,1,0]
	v_fma_mix_f32 v22, v22, v199, 0 op_sel_hi:[0,1,0]
	v_fma_mix_f32 v23, v23, v199, 0 op_sel:[0,1,0] op_sel_hi:[0,1,0]
	v_fma_mix_f32 v16, v16, v200, 0 op_sel_hi:[0,1,0]
	v_fma_mix_f32 v17, v17, v200, 0 op_sel:[0,1,0] op_sel_hi:[0,1,0]
	v_fma_mix_f32 v18, v18, v201, 0 op_sel_hi:[0,1,0]
	v_fma_mix_f32 v19, v19, v201, 0 op_sel:[0,1,0] op_sel_hi:[0,1,0]
	s_waitcnt vmcnt(1)
	v_fma_mix_f32 v12, v12, v204, 0 op_sel_hi:[0,1,0]
	v_fma_mix_f32 v13, v13, v204, 0 op_sel:[0,1,0] op_sel_hi:[0,1,0]
	v_fma_mix_f32 v14, v14, v205, 0 op_sel_hi:[0,1,0]
	v_fma_mix_f32 v15, v15, v205, 0 op_sel:[0,1,0] op_sel_hi:[0,1,0]
	v_fma_mix_f32 v8, v8, v206, 0 op_sel_hi:[0,1,0]
	v_fma_mix_f32 v9, v9, v206, 0 op_sel:[0,1,0] op_sel_hi:[0,1,0]
	v_fma_mix_f32 v10, v10, v207, 0 op_sel_hi:[0,1,0]
	v_fma_mix_f32 v11, v11, v207, 0 op_sel:[0,1,0] op_sel_hi:[0,1,0]
	s_waitcnt vmcnt(0)
	v_fma_mix_f32 v4, v4, v208, 0 op_sel_hi:[0,1,0]
	v_fma_mix_f32 v5, v5, v208, 0 op_sel:[0,1,0] op_sel_hi:[0,1,0]
	v_fma_mix_f32 v6, v6, v209, 0 op_sel_hi:[0,1,0]
	v_fma_mix_f32 v7, v7, v209, 0 op_sel:[0,1,0] op_sel_hi:[0,1,0]
	v_fma_mix_f32 v0, v0, v210, 0 op_sel_hi:[0,1,0]
	v_fma_mix_f32 v1, v1, v210, 0 op_sel:[0,1,0] op_sel_hi:[0,1,0]
	v_fma_mix_f32 v2, v2, v211, 0 op_sel_hi:[0,1,0]
	v_fma_mix_f32 v3, v3, v211, 0 op_sel:[0,1,0] op_sel_hi:[0,1,0]
	s_andn2_b64 vcc, exec, s[30:31]
	s_cbranch_vccz .LBB0_222
